# phase-0 W_in conversion loop pipelined as well
# speedup vs baseline: 1.0502x; 1.0049x over previous
; #define LAS __attribute__((address_space(3)))
; __device__ __forceinline__ bf16_t f2bf(float f) { return (bf16_t)(cvt_pk_bf16(f, 0.f) & 0xffffu); }
; __device__ __forceinline__ float bf2f(bf16_t b) { return __uint_as_float(((unsigned)b) << 16); }
; #define LBAR() do { asm volatile("s_waitcnt lgkmcnt(0)" ::: "memory"); __builtin_amdgcn_s_barrier(); asm volatile("" ::: "memory"); } while (0)
; __device__ void conv_unit(LAS unsigned char* lds, const float* src, int ld, int sn0, int nvalid, int k0, int krows,
;                           bf16_t* dst, int dn0, int Kdst, int kd0, const float* gs, const float* bs, float* c1, float* c2) {
;     ...
;     { const int k = k0 + kl; gn = gs ? gs[k] : 1.f; bn = bs ? bs[k] : 0.f;
; #pragma unroll
;       for (int j = 0; j < 8; ++j) wn[j] = (ng + j < nvalid) ? src[(size_t)k * ld + sn0 + ng + j] : 0.f; }
;     for (int kt = 0; kt < nkt; ++kt) {
;         float w[8]; const float g = gn, b = bn;
; #pragma unroll
;         for (int j = 0; j < 8; ++j) w[j] = wn[j];
;         if (kt + 1 < nkt) { const int k = k0 + (kt + 1) * 64 + kl; gn = gs ? gs[k] : 1.f; bn = bs ? bs[k] : 0.f;
; #pragma unroll
;             for (int j = 0; j < 8; ++j) wn[j] = (ng + j < nvalid) ? src[(size_t)k * ld + sn0 + ng + j] : 0.f; }
; #pragma unroll
;         for (int j = 0; j < 8; ++j) { const bf16_t wb = f2bf(w[j] * g); a1[j] += bf2f(wb); a2[j] += b * w[j]; T[(ng + j) * 72 + kl] = wb; }
;         LBAR();
;         { const int n = tid >> 3, ks = (tid & 7) * 8; const u32x4 v = *(const LAS u32x4*)(T + n * 72 + ks);
;           *(u32x4*)(dst + (size_t)(dn0 + n) * Kdst + kd0 + kt * 64 + ks) = v; }
;         LBAR();
;     }
.LBB0_995:
	s_mul_i32 s64, s19, 0xc06000
	s_mul_hi_i32 s65, s19, 0xc06000
	s_waitcnt lgkmcnt(0)
	s_add_u32 s14, s62, s64
	s_addc_u32 s15, s63, s65
	v_lshlrev_b32_e32 v0, 3, v17
	v_mov_b64_e32 v[2:3], s[14:15]
	s_movk_i32 s14, 0x3018
	v_and_b32_e32 v23, 56, v0
	v_mad_i64_i32 v[2:3], s[14:15], v14, s14, v[2:3]
	v_lshl_add_u64 v[2:3], s[90:91], 2, v[2:3]
	v_lshlrev_b32_e32 v0, 2, v23
	v_lshl_add_u64 v[8:9], v[2:3], 0, v[0:1]
	v_mov_b32_e32 v2, 0
	v_add_u32_e32 v10, s12, v14
	v_ashrrev_i32_e32 v11, 31, v10
	s_movk_i32 s13, 0x3018
	s_add_u32 s34, s56, 0x2080000
	v_lshlrev_b64 v[10:11], 11, v[10:11]
	v_and_b32_e32 v18, 7, v17
	v_mad_i64_i32 v[8:9], s[14:15], v14, s13, 0
	s_addc_u32 s35, s57, 0
	v_lshl_or_b32 v10, v18, 4, v10
	v_lshl_add_u64 v[42:43], s[34:35], 0, v[10:11]
	v_lshlrev_b64 v[10:11], 2, v[14:15]
	s_lshl_b64 s[14:15], s[90:91], 2
	v_lshl_add_u64 v[44:45], s[60:61], 0, v[10:11]
	v_lshl_add_u64 v[46:47], s[36:37], 0, v[10:11]
	v_lshl_add_u64 v[8:9], s[64:65], 0, v[8:9]
	v_lshlrev_b32_e32 v10, 5, v18
	v_mov_b32_e32 v11, v1
	s_add_u32 s14, s62, s14
	v_lshl_add_u64 v[8:9], v[8:9], 0, v[10:11]
	s_addc_u32 s15, s63, s15
	v_lshl_add_u32 v3, v23, 1, 0
	v_lshl_add_u32 v12, v14, 1, 0
	v_mul_lo_u32 v13, v14, s10
	v_mul_u32_u24_e32 v16, 0x90, v23
	v_lshl_add_u64 v[8:9], s[14:15], 0, v[8:9]
	s_mov_b64 s[14:15], 0x10
	v_lshl_add_u64 v[50:51], v[8:9], 0, s[14:15]
	s_mov_b64 s[36:37], 0x100
	v_add_u32_e32 v55, v12, v16
	v_add_u32_e32 v15, v3, v13
	v_mov_b32_e32 v3, v2
	v_mov_b32_e32 v8, v2
	v_mov_b32_e32 v9, v2
	v_mov_b32_e32 v10, v2
	v_mov_b32_e32 v11, v2
	v_mov_b32_e32 v12, v2
	v_mov_b32_e32 v13, v2
	v_mov_b32_e32 v48, v2
	v_mov_b32_e32 v49, v2
	v_mov_b32_e32 v40, v2
	v_mov_b32_e32 v41, v2
	v_mov_b32_e32 v38, v2
	v_mov_b32_e32 v39, v2
	v_mov_b32_e32 v34, v2
	v_mov_b32_e32 v35, v2
	v_mov_b32_e32 v144, 1.0
	v_mov_b32_e32 v146, 0
	v_and_b32_e32 v88, 7, v198
	v_lshl_add_u32 v92, v88, 4, v55
	v_lshrrev_b32_e32 v88, 6, v198
	v_lshl_add_u32 v93, v88, 4, v15
	global_load_dwordx2 v[30:31], v[50:51], off offset:-16
	global_load_dwordx2 v[32:33], v[50:51], off offset:-8
	global_load_dwordx2 v[36:37], v[50:51], off
	global_load_dwordx2 v[56:57], v[50:51], off offset:8
	v_lshl_add_u64 v[50:51], v[50:51], 0, s[2:3]
	global_load_dwordx2 v[138:139], v[50:51], off offset:-16
	global_load_dwordx2 v[140:141], v[50:51], off offset:-8
	global_load_dwordx2 v[142:143], v[50:51], off
	global_load_dwordx2 v[148:149], v[50:51], off offset:8
	v_lshl_add_u64 v[50:51], v[50:51], 0, s[2:3]
	global_load_dwordx2 v[150:151], v[50:51], off offset:-16
	global_load_dwordx2 v[152:153], v[50:51], off offset:-8
	global_load_dwordx2 v[154:155], v[50:51], off
	global_load_dwordx2 v[160:161], v[50:51], off offset:8
	v_lshl_add_u64 v[50:51], v[50:51], 0, s[2:3]
	global_load_dwordx2 v[18:19], v[50:51], off offset:-16
	global_load_dwordx2 v[20:21], v[50:51], off offset:-8
	global_load_dwordx2 v[24:25], v[50:51], off
	global_load_dwordx2 v[28:29], v[50:51], off offset:8
	v_lshl_add_u64 v[50:51], v[50:51], 0, s[2:3]
	s_waitcnt vmcnt(12)
	v_pk_mul_f32 v[162:163], v[30:31], v[144:145] op_sel_hi:[1,0]
	v_cvt_pk_bf16_f32 v164, v162, v163
	v_pk_fma_f32 v[2:3], v[30:31], v[146:147], v[2:3] op_sel_hi:[1,0,1]
	v_lshlrev_b32_e32 v166, 16, v164
	v_and_b32_e32 v167, 0xffff0000, v164
	v_lshrrev_b32_e32 v165, 16, v164
	ds_write_b16 v92, v164
	ds_write_b16 v92, v165 offset:144
	v_pk_add_f32 v[48:49], v[48:49], v[166:167]
	v_pk_mul_f32 v[168:169], v[32:33], v[144:145] op_sel_hi:[1,0]
	v_cvt_pk_bf16_f32 v134, v168, v169
	v_pk_fma_f32 v[8:9], v[32:33], v[146:147], v[8:9] op_sel_hi:[1,0,1]
	v_lshlrev_b32_e32 v58, 16, v134
	v_and_b32_e32 v59, 0xffff0000, v134
	v_lshrrev_b32_e32 v135, 16, v134
	ds_write_b16 v92, v134 offset:288
	ds_write_b16 v92, v135 offset:432
	v_pk_add_f32 v[40:41], v[40:41], v[58:59]
	v_pk_mul_f32 v[162:163], v[36:37], v[144:145] op_sel_hi:[1,0]
	v_cvt_pk_bf16_f32 v164, v162, v163
	v_pk_fma_f32 v[10:11], v[36:37], v[146:147], v[10:11] op_sel_hi:[1,0,1]
	v_lshlrev_b32_e32 v166, 16, v164
	v_and_b32_e32 v167, 0xffff0000, v164
	v_lshrrev_b32_e32 v165, 16, v164
	ds_write_b16 v92, v164 offset:576
	ds_write_b16 v92, v165 offset:720
	v_pk_add_f32 v[38:39], v[38:39], v[166:167]
	v_pk_mul_f32 v[168:169], v[56:57], v[144:145] op_sel_hi:[1,0]
	v_cvt_pk_bf16_f32 v134, v168, v169
	v_pk_fma_f32 v[12:13], v[56:57], v[146:147], v[12:13] op_sel_hi:[1,0,1]
	v_lshlrev_b32_e32 v58, 16, v134
	v_and_b32_e32 v59, 0xffff0000, v134
	v_lshrrev_b32_e32 v135, 16, v134
	ds_write_b16 v92, v134 offset:864
	ds_write_b16 v92, v135 offset:1008
	v_pk_add_f32 v[34:35], v[34:35], v[58:59]
	s_waitcnt lgkmcnt(0)
	s_barrier
	ds_read_b128 v[88:91], v93
	global_load_dwordx2 v[30:31], v[50:51], off offset:-16
	global_load_dwordx2 v[32:33], v[50:51], off offset:-8
	global_load_dwordx2 v[36:37], v[50:51], off
	global_load_dwordx2 v[56:57], v[50:51], off offset:8
	v_lshl_add_u64 v[50:51], v[50:51], 0, s[2:3]
	s_waitcnt lgkmcnt(0)
	global_store_dwordx4 v[42:43], v[88:91], off
	s_waitcnt vmcnt(13)
	v_pk_mul_f32 v[162:163], v[138:139], v[144:145] op_sel_hi:[1,0]
	v_cvt_pk_bf16_f32 v164, v162, v163
	v_pk_fma_f32 v[2:3], v[138:139], v[146:147], v[2:3] op_sel_hi:[1,0,1]
	v_lshlrev_b32_e32 v166, 16, v164
	v_and_b32_e32 v167, 0xffff0000, v164
	v_lshrrev_b32_e32 v165, 16, v164
	ds_write_b16 v92, v164 offset:9472
	ds_write_b16 v92, v165 offset:9616
	v_pk_add_f32 v[48:49], v[48:49], v[166:167]
	v_pk_mul_f32 v[168:169], v[140:141], v[144:145] op_sel_hi:[1,0]
	v_cvt_pk_bf16_f32 v134, v168, v169
	v_pk_fma_f32 v[8:9], v[140:141], v[146:147], v[8:9] op_sel_hi:[1,0,1]
	v_lshlrev_b32_e32 v58, 16, v134
	v_and_b32_e32 v59, 0xffff0000, v134
	v_lshrrev_b32_e32 v135, 16, v134
	ds_write_b16 v92, v134 offset:9760
	ds_write_b16 v92, v135 offset:9904
	v_pk_add_f32 v[40:41], v[40:41], v[58:59]
	v_pk_mul_f32 v[162:163], v[142:143], v[144:145] op_sel_hi:[1,0]
	v_cvt_pk_bf16_f32 v164, v162, v163
	v_pk_fma_f32 v[10:11], v[142:143], v[146:147], v[10:11] op_sel_hi:[1,0,1]
	v_lshlrev_b32_e32 v166, 16, v164
	v_and_b32_e32 v167, 0xffff0000, v164
	v_lshrrev_b32_e32 v165, 16, v164
	ds_write_b16 v92, v164 offset:10048
	ds_write_b16 v92, v165 offset:10192
	v_pk_add_f32 v[38:39], v[38:39], v[166:167]
	v_pk_mul_f32 v[168:169], v[148:149], v[144:145] op_sel_hi:[1,0]
	v_cvt_pk_bf16_f32 v134, v168, v169
	v_pk_fma_f32 v[12:13], v[148:149], v[146:147], v[12:13] op_sel_hi:[1,0,1]
	v_lshlrev_b32_e32 v58, 16, v134
	v_and_b32_e32 v59, 0xffff0000, v134
	v_lshrrev_b32_e32 v135, 16, v134
	ds_write_b16 v92, v134 offset:10336
	ds_write_b16 v92, v135 offset:10480
	v_pk_add_f32 v[34:35], v[34:35], v[58:59]
	s_waitcnt lgkmcnt(0)
	s_barrier
; #define LAS __attribute__((address_space(3)))
; __device__ __forceinline__ bf16_t f2bf(float f) { return (bf16_t)(cvt_pk_bf16(f, 0.f) & 0xffffu); }
; __device__ __forceinline__ float bf2f(bf16_t b) { return __uint_as_float(((unsigned)b) << 16); }
; #define LBAR() do { asm volatile("s_waitcnt lgkmcnt(0)" ::: "memory"); __builtin_amdgcn_s_barrier(); asm volatile("" ::: "memory"); } while (0)
; __device__ void conv_unit(LAS unsigned char* lds, const float* src, int ld, int sn0, int nvalid, int k0, int krows,
;                           bf16_t* dst, int dn0, int Kdst, int kd0, const float* gs, const float* bs, float* c1, float* c2) {
;     ...
;     for (int kt = 0; kt < nkt; ++kt) {
;         float w[8]; const float g = gn, b = bn;
; #pragma unroll
;         for (int j = 0; j < 8; ++j) w[j] = wn[j];
;         if (kt + 1 < nkt) { const int k = k0 + (kt + 1) * 64 + kl; gn = gs ? gs[k] : 1.f; bn = bs ? bs[k] : 0.f;
; #pragma unroll
;             for (int j = 0; j < 8; ++j) wn[j] = (ng + j < nvalid) ? src[(size_t)k * ld + sn0 + ng + j] : 0.f; }
; #pragma unroll
;         for (int j = 0; j < 8; ++j) { const bf16_t wb = f2bf(w[j] * g); a1[j] += bf2f(wb); a2[j] += b * w[j]; T[(ng + j) * 72 + kl] = wb; }
;         LBAR();
;         { const int n = tid >> 3, ks = (tid & 7) * 8; const u32x4 v = *(const LAS u32x4*)(T + n * 72 + ks);
;           *(u32x4*)(dst + (size_t)(dn0 + n) * Kdst + kd0 + kt * 64 + ks) = v; }
;         LBAR();
;     }
	ds_read_b128 v[184:187], v93 offset:9472
	global_load_dwordx2 v[138:139], v[50:51], off offset:-16
	global_load_dwordx2 v[140:141], v[50:51], off offset:-8
	global_load_dwordx2 v[142:143], v[50:51], off
	global_load_dwordx2 v[148:149], v[50:51], off offset:8
	v_lshl_add_u64 v[50:51], v[50:51], 0, s[2:3]
	s_waitcnt lgkmcnt(0)
	global_store_dwordx4 v[42:43], v[184:187], off offset:128
	s_waitcnt vmcnt(14)
	v_pk_mul_f32 v[162:163], v[150:151], v[144:145] op_sel_hi:[1,0]
	v_cvt_pk_bf16_f32 v164, v162, v163
	v_pk_fma_f32 v[2:3], v[150:151], v[146:147], v[2:3] op_sel_hi:[1,0,1]
	v_lshlrev_b32_e32 v166, 16, v164
	v_and_b32_e32 v167, 0xffff0000, v164
	v_lshrrev_b32_e32 v165, 16, v164
	ds_write_b16 v92, v164
	ds_write_b16 v92, v165 offset:144
	v_pk_add_f32 v[48:49], v[48:49], v[166:167]
	v_pk_mul_f32 v[168:169], v[152:153], v[144:145] op_sel_hi:[1,0]
	v_cvt_pk_bf16_f32 v134, v168, v169
	v_pk_fma_f32 v[8:9], v[152:153], v[146:147], v[8:9] op_sel_hi:[1,0,1]
	v_lshlrev_b32_e32 v58, 16, v134
	v_and_b32_e32 v59, 0xffff0000, v134
	v_lshrrev_b32_e32 v135, 16, v134
	ds_write_b16 v92, v134 offset:288
	ds_write_b16 v92, v135 offset:432
	v_pk_add_f32 v[40:41], v[40:41], v[58:59]
	v_pk_mul_f32 v[162:163], v[154:155], v[144:145] op_sel_hi:[1,0]
	v_cvt_pk_bf16_f32 v164, v162, v163
	v_pk_fma_f32 v[10:11], v[154:155], v[146:147], v[10:11] op_sel_hi:[1,0,1]
	v_lshlrev_b32_e32 v166, 16, v164
	v_and_b32_e32 v167, 0xffff0000, v164
	v_lshrrev_b32_e32 v165, 16, v164
	ds_write_b16 v92, v164 offset:576
	ds_write_b16 v92, v165 offset:720
	v_pk_add_f32 v[38:39], v[38:39], v[166:167]
	v_pk_mul_f32 v[168:169], v[160:161], v[144:145] op_sel_hi:[1,0]
	v_cvt_pk_bf16_f32 v134, v168, v169
	v_pk_fma_f32 v[12:13], v[160:161], v[146:147], v[12:13] op_sel_hi:[1,0,1]
	v_lshlrev_b32_e32 v58, 16, v134
	v_and_b32_e32 v59, 0xffff0000, v134
	v_lshrrev_b32_e32 v135, 16, v134
	ds_write_b16 v92, v134 offset:864
	ds_write_b16 v92, v135 offset:1008
	v_pk_add_f32 v[34:35], v[34:35], v[58:59]
	s_waitcnt lgkmcnt(0)
	s_barrier
	ds_read_b128 v[88:91], v93
	global_load_dwordx2 v[150:151], v[50:51], off offset:-16
	global_load_dwordx2 v[152:153], v[50:51], off offset:-8
	global_load_dwordx2 v[154:155], v[50:51], off
	global_load_dwordx2 v[160:161], v[50:51], off offset:8
	v_lshl_add_u64 v[50:51], v[50:51], 0, s[2:3]
	s_waitcnt lgkmcnt(0)
	global_store_dwordx4 v[42:43], v[88:91], off offset:256
	s_waitcnt vmcnt(15)
	v_pk_mul_f32 v[162:163], v[18:19], v[144:145] op_sel_hi:[1,0]
	v_cvt_pk_bf16_f32 v164, v162, v163
	v_pk_fma_f32 v[2:3], v[18:19], v[146:147], v[2:3] op_sel_hi:[1,0,1]
	v_lshlrev_b32_e32 v166, 16, v164
	v_and_b32_e32 v167, 0xffff0000, v164
	v_lshrrev_b32_e32 v165, 16, v164
	ds_write_b16 v92, v164 offset:9472
	ds_write_b16 v92, v165 offset:9616
	v_pk_add_f32 v[48:49], v[48:49], v[166:167]
	v_pk_mul_f32 v[168:169], v[20:21], v[144:145] op_sel_hi:[1,0]
	v_cvt_pk_bf16_f32 v134, v168, v169
	v_pk_fma_f32 v[8:9], v[20:21], v[146:147], v[8:9] op_sel_hi:[1,0,1]
	v_lshlrev_b32_e32 v58, 16, v134
	v_and_b32_e32 v59, 0xffff0000, v134
	v_lshrrev_b32_e32 v135, 16, v134
	ds_write_b16 v92, v134 offset:9760
	ds_write_b16 v92, v135 offset:9904
	v_pk_add_f32 v[40:41], v[40:41], v[58:59]
	v_pk_mul_f32 v[162:163], v[24:25], v[144:145] op_sel_hi:[1,0]
	v_cvt_pk_bf16_f32 v164, v162, v163
	v_pk_fma_f32 v[10:11], v[24:25], v[146:147], v[10:11] op_sel_hi:[1,0,1]
	v_lshlrev_b32_e32 v166, 16, v164
	v_and_b32_e32 v167, 0xffff0000, v164
	v_lshrrev_b32_e32 v165, 16, v164
	ds_write_b16 v92, v164 offset:10048
	ds_write_b16 v92, v165 offset:10192
	v_pk_add_f32 v[38:39], v[38:39], v[166:167]
	v_pk_mul_f32 v[168:169], v[28:29], v[144:145] op_sel_hi:[1,0]
	v_cvt_pk_bf16_f32 v134, v168, v169
	v_pk_fma_f32 v[12:13], v[28:29], v[146:147], v[12:13] op_sel_hi:[1,0,1]
	v_lshlrev_b32_e32 v58, 16, v134
	v_and_b32_e32 v59, 0xffff0000, v134
	v_lshrrev_b32_e32 v135, 16, v134
	ds_write_b16 v92, v134 offset:10336
	ds_write_b16 v92, v135 offset:10480
	v_pk_add_f32 v[34:35], v[34:35], v[58:59]
	s_waitcnt lgkmcnt(0)
	s_barrier
	ds_read_b128 v[184:187], v93 offset:9472
	global_load_dwordx2 v[18:19], v[50:51], off offset:-16
	global_load_dwordx2 v[20:21], v[50:51], off offset:-8
	global_load_dwordx2 v[24:25], v[50:51], off
	global_load_dwordx2 v[28:29], v[50:51], off offset:8
	v_lshl_add_u64 v[50:51], v[50:51], 0, s[2:3]
	s_waitcnt lgkmcnt(0)
	global_store_dwordx4 v[42:43], v[184:187], off offset:384
	s_waitcnt vmcnt(16)
	v_pk_mul_f32 v[162:163], v[30:31], v[144:145] op_sel_hi:[1,0]
	v_cvt_pk_bf16_f32 v164, v162, v163
	v_pk_fma_f32 v[2:3], v[30:31], v[146:147], v[2:3] op_sel_hi:[1,0,1]
	v_lshlrev_b32_e32 v166, 16, v164
	v_and_b32_e32 v167, 0xffff0000, v164
	v_lshrrev_b32_e32 v165, 16, v164
	ds_write_b16 v92, v164
	ds_write_b16 v92, v165 offset:144
	v_pk_add_f32 v[48:49], v[48:49], v[166:167]
	v_pk_mul_f32 v[168:169], v[32:33], v[144:145] op_sel_hi:[1,0]
	v_cvt_pk_bf16_f32 v134, v168, v169
	v_pk_fma_f32 v[8:9], v[32:33], v[146:147], v[8:9] op_sel_hi:[1,0,1]
	v_lshlrev_b32_e32 v58, 16, v134
	v_and_b32_e32 v59, 0xffff0000, v134
	v_lshrrev_b32_e32 v135, 16, v134
	ds_write_b16 v92, v134 offset:288
	ds_write_b16 v92, v135 offset:432
	v_pk_add_f32 v[40:41], v[40:41], v[58:59]
	v_pk_mul_f32 v[162:163], v[36:37], v[144:145] op_sel_hi:[1,0]
	v_cvt_pk_bf16_f32 v164, v162, v163
	v_pk_fma_f32 v[10:11], v[36:37], v[146:147], v[10:11] op_sel_hi:[1,0,1]
	v_lshlrev_b32_e32 v166, 16, v164
	v_and_b32_e32 v167, 0xffff0000, v164
	v_lshrrev_b32_e32 v165, 16, v164
	ds_write_b16 v92, v164 offset:576
	ds_write_b16 v92, v165 offset:720
	v_pk_add_f32 v[38:39], v[38:39], v[166:167]
	v_pk_mul_f32 v[168:169], v[56:57], v[144:145] op_sel_hi:[1,0]
	v_cvt_pk_bf16_f32 v134, v168, v169
	v_pk_fma_f32 v[12:13], v[56:57], v[146:147], v[12:13] op_sel_hi:[1,0,1]
	v_lshlrev_b32_e32 v58, 16, v134
	v_and_b32_e32 v59, 0xffff0000, v134
	v_lshrrev_b32_e32 v135, 16, v134
	ds_write_b16 v92, v134 offset:864
	ds_write_b16 v92, v135 offset:1008
	v_pk_add_f32 v[34:35], v[34:35], v[58:59]
	s_waitcnt lgkmcnt(0)
	s_barrier
; #define LAS __attribute__((address_space(3)))
; __device__ __forceinline__ bf16_t f2bf(float f) { return (bf16_t)(cvt_pk_bf16(f, 0.f) & 0xffffu); }
; __device__ __forceinline__ float bf2f(bf16_t b) { return __uint_as_float(((unsigned)b) << 16); }
; #define LBAR() do { asm volatile("s_waitcnt lgkmcnt(0)" ::: "memory"); __builtin_amdgcn_s_barrier(); asm volatile("" ::: "memory"); } while (0)
; __device__ void conv_unit(LAS unsigned char* lds, const float* src, int ld, int sn0, int nvalid, int k0, int krows,
;                           bf16_t* dst, int dn0, int Kdst, int kd0, const float* gs, const float* bs, float* c1, float* c2) {
;     ...
;     for (int kt = 0; kt < nkt; ++kt) {
;         float w[8]; const float g = gn, b = bn;
; #pragma unroll
;         for (int j = 0; j < 8; ++j) w[j] = wn[j];
;         if (kt + 1 < nkt) { const int k = k0 + (kt + 1) * 64 + kl; gn = gs ? gs[k] : 1.f; bn = bs ? bs[k] : 0.f;
; #pragma unroll
;             for (int j = 0; j < 8; ++j) wn[j] = (ng + j < nvalid) ? src[(size_t)k * ld + sn0 + ng + j] : 0.f; }
; #pragma unroll
;         for (int j = 0; j < 8; ++j) { const bf16_t wb = f2bf(w[j] * g); a1[j] += bf2f(wb); a2[j] += b * w[j]; T[(ng + j) * 72 + kl] = wb; }
;         LBAR();
;         { const int n = tid >> 3, ks = (tid & 7) * 8; const u32x4 v = *(const LAS u32x4*)(T + n * 72 + ks);
;           *(u32x4*)(dst + (size_t)(dn0 + n) * Kdst + kd0 + kt * 64 + ks) = v; }
;         LBAR();
;     }
	ds_read_b128 v[88:91], v93
	global_load_dwordx2 v[30:31], v[50:51], off offset:-16
	global_load_dwordx2 v[32:33], v[50:51], off offset:-8
	global_load_dwordx2 v[36:37], v[50:51], off
	global_load_dwordx2 v[56:57], v[50:51], off offset:8
	v_lshl_add_u64 v[50:51], v[50:51], 0, s[2:3]
	s_waitcnt lgkmcnt(0)
	global_store_dwordx4 v[42:43], v[88:91], off offset:512
	s_waitcnt vmcnt(16)
	v_pk_mul_f32 v[162:163], v[138:139], v[144:145] op_sel_hi:[1,0]
	v_cvt_pk_bf16_f32 v164, v162, v163
	v_pk_fma_f32 v[2:3], v[138:139], v[146:147], v[2:3] op_sel_hi:[1,0,1]
	v_lshlrev_b32_e32 v166, 16, v164
	v_and_b32_e32 v167, 0xffff0000, v164
	v_lshrrev_b32_e32 v165, 16, v164
	ds_write_b16 v92, v164 offset:9472
	ds_write_b16 v92, v165 offset:9616
	v_pk_add_f32 v[48:49], v[48:49], v[166:167]
	v_pk_mul_f32 v[168:169], v[140:141], v[144:145] op_sel_hi:[1,0]
	v_cvt_pk_bf16_f32 v134, v168, v169
	v_pk_fma_f32 v[8:9], v[140:141], v[146:147], v[8:9] op_sel_hi:[1,0,1]
	v_lshlrev_b32_e32 v58, 16, v134
	v_and_b32_e32 v59, 0xffff0000, v134
	v_lshrrev_b32_e32 v135, 16, v134
	ds_write_b16 v92, v134 offset:9760
	ds_write_b16 v92, v135 offset:9904
	v_pk_add_f32 v[40:41], v[40:41], v[58:59]
	v_pk_mul_f32 v[162:163], v[142:143], v[144:145] op_sel_hi:[1,0]
	v_cvt_pk_bf16_f32 v164, v162, v163
	v_pk_fma_f32 v[10:11], v[142:143], v[146:147], v[10:11] op_sel_hi:[1,0,1]
	v_lshlrev_b32_e32 v166, 16, v164
	v_and_b32_e32 v167, 0xffff0000, v164
	v_lshrrev_b32_e32 v165, 16, v164
	ds_write_b16 v92, v164 offset:10048
	ds_write_b16 v92, v165 offset:10192
	v_pk_add_f32 v[38:39], v[38:39], v[166:167]
	v_pk_mul_f32 v[168:169], v[148:149], v[144:145] op_sel_hi:[1,0]
	v_cvt_pk_bf16_f32 v134, v168, v169
	v_pk_fma_f32 v[12:13], v[148:149], v[146:147], v[12:13] op_sel_hi:[1,0,1]
	v_lshlrev_b32_e32 v58, 16, v134
	v_and_b32_e32 v59, 0xffff0000, v134
	v_lshrrev_b32_e32 v135, 16, v134
	ds_write_b16 v92, v134 offset:10336
	ds_write_b16 v92, v135 offset:10480
	v_pk_add_f32 v[34:35], v[34:35], v[58:59]
	s_waitcnt lgkmcnt(0)
	s_barrier
	ds_read_b128 v[184:187], v93 offset:9472
	global_load_dwordx2 v[138:139], v[50:51], off offset:-16
	global_load_dwordx2 v[140:141], v[50:51], off offset:-8
	global_load_dwordx2 v[142:143], v[50:51], off
	global_load_dwordx2 v[148:149], v[50:51], off offset:8
	v_lshl_add_u64 v[50:51], v[50:51], 0, s[2:3]
	s_waitcnt lgkmcnt(0)
	global_store_dwordx4 v[42:43], v[184:187], off offset:640
	s_waitcnt vmcnt(16)
	v_pk_mul_f32 v[162:163], v[150:151], v[144:145] op_sel_hi:[1,0]
	v_cvt_pk_bf16_f32 v164, v162, v163
	v_pk_fma_f32 v[2:3], v[150:151], v[146:147], v[2:3] op_sel_hi:[1,0,1]
	v_lshlrev_b32_e32 v166, 16, v164
	v_and_b32_e32 v167, 0xffff0000, v164
	v_lshrrev_b32_e32 v165, 16, v164
	ds_write_b16 v92, v164
	ds_write_b16 v92, v165 offset:144
	v_pk_add_f32 v[48:49], v[48:49], v[166:167]
	v_pk_mul_f32 v[168:169], v[152:153], v[144:145] op_sel_hi:[1,0]
	v_cvt_pk_bf16_f32 v134, v168, v169
	v_pk_fma_f32 v[8:9], v[152:153], v[146:147], v[8:9] op_sel_hi:[1,0,1]
	v_lshlrev_b32_e32 v58, 16, v134
	v_and_b32_e32 v59, 0xffff0000, v134
	v_lshrrev_b32_e32 v135, 16, v134
	ds_write_b16 v92, v134 offset:288
	ds_write_b16 v92, v135 offset:432
	v_pk_add_f32 v[40:41], v[40:41], v[58:59]
	v_pk_mul_f32 v[162:163], v[154:155], v[144:145] op_sel_hi:[1,0]
	v_cvt_pk_bf16_f32 v164, v162, v163
	v_pk_fma_f32 v[10:11], v[154:155], v[146:147], v[10:11] op_sel_hi:[1,0,1]
	v_lshlrev_b32_e32 v166, 16, v164
	v_and_b32_e32 v167, 0xffff0000, v164
	v_lshrrev_b32_e32 v165, 16, v164
	ds_write_b16 v92, v164 offset:576
	ds_write_b16 v92, v165 offset:720
	v_pk_add_f32 v[38:39], v[38:39], v[166:167]
	v_pk_mul_f32 v[168:169], v[160:161], v[144:145] op_sel_hi:[1,0]
	v_cvt_pk_bf16_f32 v134, v168, v169
	v_pk_fma_f32 v[12:13], v[160:161], v[146:147], v[12:13] op_sel_hi:[1,0,1]
	v_lshlrev_b32_e32 v58, 16, v134
	v_and_b32_e32 v59, 0xffff0000, v134
	v_lshrrev_b32_e32 v135, 16, v134
	ds_write_b16 v92, v134 offset:864
	ds_write_b16 v92, v135 offset:1008
	v_pk_add_f32 v[34:35], v[34:35], v[58:59]
	s_waitcnt lgkmcnt(0)
	s_barrier
	ds_read_b128 v[88:91], v93
	global_load_dwordx2 v[150:151], v[50:51], off offset:-16
	global_load_dwordx2 v[152:153], v[50:51], off offset:-8
	global_load_dwordx2 v[154:155], v[50:51], off
	global_load_dwordx2 v[160:161], v[50:51], off offset:8
	v_lshl_add_u64 v[50:51], v[50:51], 0, s[2:3]
	s_waitcnt lgkmcnt(0)
	global_store_dwordx4 v[42:43], v[88:91], off offset:768
	s_waitcnt vmcnt(16)
	v_pk_mul_f32 v[162:163], v[18:19], v[144:145] op_sel_hi:[1,0]
	v_cvt_pk_bf16_f32 v164, v162, v163
	v_pk_fma_f32 v[2:3], v[18:19], v[146:147], v[2:3] op_sel_hi:[1,0,1]
	v_lshlrev_b32_e32 v166, 16, v164
	v_and_b32_e32 v167, 0xffff0000, v164
	v_lshrrev_b32_e32 v165, 16, v164
	ds_write_b16 v92, v164 offset:9472
	ds_write_b16 v92, v165 offset:9616
	v_pk_add_f32 v[48:49], v[48:49], v[166:167]
	v_pk_mul_f32 v[168:169], v[20:21], v[144:145] op_sel_hi:[1,0]
	v_cvt_pk_bf16_f32 v134, v168, v169
	v_pk_fma_f32 v[8:9], v[20:21], v[146:147], v[8:9] op_sel_hi:[1,0,1]
	v_lshlrev_b32_e32 v58, 16, v134
	v_and_b32_e32 v59, 0xffff0000, v134
	v_lshrrev_b32_e32 v135, 16, v134
	ds_write_b16 v92, v134 offset:9760
	ds_write_b16 v92, v135 offset:9904
	v_pk_add_f32 v[40:41], v[40:41], v[58:59]
	v_pk_mul_f32 v[162:163], v[24:25], v[144:145] op_sel_hi:[1,0]
	v_cvt_pk_bf16_f32 v164, v162, v163
	v_pk_fma_f32 v[10:11], v[24:25], v[146:147], v[10:11] op_sel_hi:[1,0,1]
	v_lshlrev_b32_e32 v166, 16, v164
	v_and_b32_e32 v167, 0xffff0000, v164
	v_lshrrev_b32_e32 v165, 16, v164
	ds_write_b16 v92, v164 offset:10048
	ds_write_b16 v92, v165 offset:10192
	v_pk_add_f32 v[38:39], v[38:39], v[166:167]
	v_pk_mul_f32 v[168:169], v[28:29], v[144:145] op_sel_hi:[1,0]
	v_cvt_pk_bf16_f32 v134, v168, v169
	v_pk_fma_f32 v[12:13], v[28:29], v[146:147], v[12:13] op_sel_hi:[1,0,1]
	v_lshlrev_b32_e32 v58, 16, v134
	v_and_b32_e32 v59, 0xffff0000, v134
	v_lshrrev_b32_e32 v135, 16, v134
	ds_write_b16 v92, v134 offset:10336
	ds_write_b16 v92, v135 offset:10480
	v_pk_add_f32 v[34:35], v[34:35], v[58:59]
	s_waitcnt lgkmcnt(0)
	s_barrier
; #define LAS __attribute__((address_space(3)))
; __device__ __forceinline__ bf16_t f2bf(float f) { return (bf16_t)(cvt_pk_bf16(f, 0.f) & 0xffffu); }
; __device__ __forceinline__ float bf2f(bf16_t b) { return __uint_as_float(((unsigned)b) << 16); }
; #define LBAR() do { asm volatile("s_waitcnt lgkmcnt(0)" ::: "memory"); __builtin_amdgcn_s_barrier(); asm volatile("" ::: "memory"); } while (0)
; __device__ void conv_unit(LAS unsigned char* lds, const float* src, int ld, int sn0, int nvalid, int k0, int krows,
;                           bf16_t* dst, int dn0, int Kdst, int kd0, const float* gs, const float* bs, float* c1, float* c2) {
;     ...
;     for (int kt = 0; kt < nkt; ++kt) {
;         float w[8]; const float g = gn, b = bn;
; #pragma unroll
;         for (int j = 0; j < 8; ++j) w[j] = wn[j];
;         if (kt + 1 < nkt) { const int k = k0 + (kt + 1) * 64 + kl; gn = gs ? gs[k] : 1.f; bn = bs ? bs[k] : 0.f;
; #pragma unroll
;             for (int j = 0; j < 8; ++j) wn[j] = (ng + j < nvalid) ? src[(size_t)k * ld + sn0 + ng + j] : 0.f; }
; #pragma unroll
;         for (int j = 0; j < 8; ++j) { const bf16_t wb = f2bf(w[j] * g); a1[j] += bf2f(wb); a2[j] += b * w[j]; T[(ng + j) * 72 + kl] = wb; }
;         LBAR();
;         { const int n = tid >> 3, ks = (tid & 7) * 8; const u32x4 v = *(const LAS u32x4*)(T + n * 72 + ks);
;           *(u32x4*)(dst + (size_t)(dn0 + n) * Kdst + kd0 + kt * 64 + ks) = v; }
;         LBAR();
;     }
	ds_read_b128 v[184:187], v93 offset:9472
	global_load_dwordx2 v[18:19], v[50:51], off offset:-16
	global_load_dwordx2 v[20:21], v[50:51], off offset:-8
	global_load_dwordx2 v[24:25], v[50:51], off
	global_load_dwordx2 v[28:29], v[50:51], off offset:8
	v_lshl_add_u64 v[50:51], v[50:51], 0, s[2:3]
	s_waitcnt lgkmcnt(0)
	global_store_dwordx4 v[42:43], v[184:187], off offset:896
	s_waitcnt vmcnt(16)
	v_pk_mul_f32 v[162:163], v[30:31], v[144:145] op_sel_hi:[1,0]
	v_cvt_pk_bf16_f32 v164, v162, v163
	v_pk_fma_f32 v[2:3], v[30:31], v[146:147], v[2:3] op_sel_hi:[1,0,1]
	v_lshlrev_b32_e32 v166, 16, v164
	v_and_b32_e32 v167, 0xffff0000, v164
	v_lshrrev_b32_e32 v165, 16, v164
	ds_write_b16 v92, v164
	ds_write_b16 v92, v165 offset:144
	v_pk_add_f32 v[48:49], v[48:49], v[166:167]
	v_pk_mul_f32 v[168:169], v[32:33], v[144:145] op_sel_hi:[1,0]
	v_cvt_pk_bf16_f32 v134, v168, v169
	v_pk_fma_f32 v[8:9], v[32:33], v[146:147], v[8:9] op_sel_hi:[1,0,1]
	v_lshlrev_b32_e32 v58, 16, v134
	v_and_b32_e32 v59, 0xffff0000, v134
	v_lshrrev_b32_e32 v135, 16, v134
	ds_write_b16 v92, v134 offset:288
	ds_write_b16 v92, v135 offset:432
	v_pk_add_f32 v[40:41], v[40:41], v[58:59]
	v_pk_mul_f32 v[162:163], v[36:37], v[144:145] op_sel_hi:[1,0]
	v_cvt_pk_bf16_f32 v164, v162, v163
	v_pk_fma_f32 v[10:11], v[36:37], v[146:147], v[10:11] op_sel_hi:[1,0,1]
	v_lshlrev_b32_e32 v166, 16, v164
	v_and_b32_e32 v167, 0xffff0000, v164
	v_lshrrev_b32_e32 v165, 16, v164
	ds_write_b16 v92, v164 offset:576
	ds_write_b16 v92, v165 offset:720
	v_pk_add_f32 v[38:39], v[38:39], v[166:167]
	v_pk_mul_f32 v[168:169], v[56:57], v[144:145] op_sel_hi:[1,0]
	v_cvt_pk_bf16_f32 v134, v168, v169
	v_pk_fma_f32 v[12:13], v[56:57], v[146:147], v[12:13] op_sel_hi:[1,0,1]
	v_lshlrev_b32_e32 v58, 16, v134
	v_and_b32_e32 v59, 0xffff0000, v134
	v_lshrrev_b32_e32 v135, 16, v134
	ds_write_b16 v92, v134 offset:864
	ds_write_b16 v92, v135 offset:1008
	v_pk_add_f32 v[34:35], v[34:35], v[58:59]
	s_waitcnt lgkmcnt(0)
	s_barrier
	ds_read_b128 v[88:91], v93
	global_load_dwordx2 v[30:31], v[50:51], off offset:-16
	global_load_dwordx2 v[32:33], v[50:51], off offset:-8
	global_load_dwordx2 v[36:37], v[50:51], off
	global_load_dwordx2 v[56:57], v[50:51], off offset:8
	v_lshl_add_u64 v[50:51], v[50:51], 0, s[2:3]
	s_waitcnt lgkmcnt(0)
	global_store_dwordx4 v[42:43], v[88:91], off offset:1024
	s_waitcnt vmcnt(16)
	v_pk_mul_f32 v[162:163], v[138:139], v[144:145] op_sel_hi:[1,0]
	v_cvt_pk_bf16_f32 v164, v162, v163
	v_pk_fma_f32 v[2:3], v[138:139], v[146:147], v[2:3] op_sel_hi:[1,0,1]
	v_lshlrev_b32_e32 v166, 16, v164
	v_and_b32_e32 v167, 0xffff0000, v164
	v_lshrrev_b32_e32 v165, 16, v164
	ds_write_b16 v92, v164 offset:9472
	ds_write_b16 v92, v165 offset:9616
	v_pk_add_f32 v[48:49], v[48:49], v[166:167]
	v_pk_mul_f32 v[168:169], v[140:141], v[144:145] op_sel_hi:[1,0]
	v_cvt_pk_bf16_f32 v134, v168, v169
	v_pk_fma_f32 v[8:9], v[140:141], v[146:147], v[8:9] op_sel_hi:[1,0,1]
	v_lshlrev_b32_e32 v58, 16, v134
	v_and_b32_e32 v59, 0xffff0000, v134
	v_lshrrev_b32_e32 v135, 16, v134
	ds_write_b16 v92, v134 offset:9760
	ds_write_b16 v92, v135 offset:9904
	v_pk_add_f32 v[40:41], v[40:41], v[58:59]
	v_pk_mul_f32 v[162:163], v[142:143], v[144:145] op_sel_hi:[1,0]
	v_cvt_pk_bf16_f32 v164, v162, v163
	v_pk_fma_f32 v[10:11], v[142:143], v[146:147], v[10:11] op_sel_hi:[1,0,1]
	v_lshlrev_b32_e32 v166, 16, v164
	v_and_b32_e32 v167, 0xffff0000, v164
	v_lshrrev_b32_e32 v165, 16, v164
	ds_write_b16 v92, v164 offset:10048
	ds_write_b16 v92, v165 offset:10192
	v_pk_add_f32 v[38:39], v[38:39], v[166:167]
	v_pk_mul_f32 v[168:169], v[148:149], v[144:145] op_sel_hi:[1,0]
	v_cvt_pk_bf16_f32 v134, v168, v169
	v_pk_fma_f32 v[12:13], v[148:149], v[146:147], v[12:13] op_sel_hi:[1,0,1]
	v_lshlrev_b32_e32 v58, 16, v134
	v_and_b32_e32 v59, 0xffff0000, v134
	v_lshrrev_b32_e32 v135, 16, v134
	ds_write_b16 v92, v134 offset:10336
	ds_write_b16 v92, v135 offset:10480
	v_pk_add_f32 v[34:35], v[34:35], v[58:59]
	s_waitcnt lgkmcnt(0)
	s_barrier
	ds_read_b128 v[184:187], v93 offset:9472
	global_load_dwordx2 v[138:139], v[50:51], off offset:-16
	global_load_dwordx2 v[140:141], v[50:51], off offset:-8
	global_load_dwordx2 v[142:143], v[50:51], off
	global_load_dwordx2 v[148:149], v[50:51], off offset:8
	v_lshl_add_u64 v[50:51], v[50:51], 0, s[2:3]
	s_waitcnt lgkmcnt(0)
	global_store_dwordx4 v[42:43], v[184:187], off offset:1152
	s_waitcnt vmcnt(16)
	v_pk_mul_f32 v[162:163], v[150:151], v[144:145] op_sel_hi:[1,0]
	v_cvt_pk_bf16_f32 v164, v162, v163
	v_pk_fma_f32 v[2:3], v[150:151], v[146:147], v[2:3] op_sel_hi:[1,0,1]
	v_lshlrev_b32_e32 v166, 16, v164
	v_and_b32_e32 v167, 0xffff0000, v164
	v_lshrrev_b32_e32 v165, 16, v164
	ds_write_b16 v92, v164
	ds_write_b16 v92, v165 offset:144
	v_pk_add_f32 v[48:49], v[48:49], v[166:167]
	v_pk_mul_f32 v[168:169], v[152:153], v[144:145] op_sel_hi:[1,0]
	v_cvt_pk_bf16_f32 v134, v168, v169
	v_pk_fma_f32 v[8:9], v[152:153], v[146:147], v[8:9] op_sel_hi:[1,0,1]
	v_lshlrev_b32_e32 v58, 16, v134
	v_and_b32_e32 v59, 0xffff0000, v134
	v_lshrrev_b32_e32 v135, 16, v134
	ds_write_b16 v92, v134 offset:288
	ds_write_b16 v92, v135 offset:432
	v_pk_add_f32 v[40:41], v[40:41], v[58:59]
	v_pk_mul_f32 v[162:163], v[154:155], v[144:145] op_sel_hi:[1,0]
	v_cvt_pk_bf16_f32 v164, v162, v163
	v_pk_fma_f32 v[10:11], v[154:155], v[146:147], v[10:11] op_sel_hi:[1,0,1]
	v_lshlrev_b32_e32 v166, 16, v164
	v_and_b32_e32 v167, 0xffff0000, v164
	v_lshrrev_b32_e32 v165, 16, v164
	ds_write_b16 v92, v164 offset:576
	ds_write_b16 v92, v165 offset:720
	v_pk_add_f32 v[38:39], v[38:39], v[166:167]
	v_pk_mul_f32 v[168:169], v[160:161], v[144:145] op_sel_hi:[1,0]
	v_cvt_pk_bf16_f32 v134, v168, v169
	v_pk_fma_f32 v[12:13], v[160:161], v[146:147], v[12:13] op_sel_hi:[1,0,1]
	v_lshlrev_b32_e32 v58, 16, v134
	v_and_b32_e32 v59, 0xffff0000, v134
	v_lshrrev_b32_e32 v135, 16, v134
	ds_write_b16 v92, v134 offset:864
	ds_write_b16 v92, v135 offset:1008
	v_pk_add_f32 v[34:35], v[34:35], v[58:59]
	s_waitcnt lgkmcnt(0)
	s_barrier
; #define LAS __attribute__((address_space(3)))
; __device__ __forceinline__ bf16_t f2bf(float f) { return (bf16_t)(cvt_pk_bf16(f, 0.f) & 0xffffu); }
; __device__ __forceinline__ float bf2f(bf16_t b) { return __uint_as_float(((unsigned)b) << 16); }
; #define LBAR() do { asm volatile("s_waitcnt lgkmcnt(0)" ::: "memory"); __builtin_amdgcn_s_barrier(); asm volatile("" ::: "memory"); } while (0)
; __device__ void conv_unit(LAS unsigned char* lds, const float* src, int ld, int sn0, int nvalid, int k0, int krows,
;                           bf16_t* dst, int dn0, int Kdst, int kd0, const float* gs, const float* bs, float* c1, float* c2) {
;     ...
;     for (int kt = 0; kt < nkt; ++kt) {
;         float w[8]; const float g = gn, b = bn;
; #pragma unroll
;         for (int j = 0; j < 8; ++j) w[j] = wn[j];
;         if (kt + 1 < nkt) { const int k = k0 + (kt + 1) * 64 + kl; gn = gs ? gs[k] : 1.f; bn = bs ? bs[k] : 0.f;
; #pragma unroll
;             for (int j = 0; j < 8; ++j) wn[j] = (ng + j < nvalid) ? src[(size_t)k * ld + sn0 + ng + j] : 0.f; }
; #pragma unroll
;         for (int j = 0; j < 8; ++j) { const bf16_t wb = f2bf(w[j] * g); a1[j] += bf2f(wb); a2[j] += b * w[j]; T[(ng + j) * 72 + kl] = wb; }
;         LBAR();
;         { const int n = tid >> 3, ks = (tid & 7) * 8; const u32x4 v = *(const LAS u32x4*)(T + n * 72 + ks);
;           *(u32x4*)(dst + (size_t)(dn0 + n) * Kdst + kd0 + kt * 64 + ks) = v; }
;         LBAR();
;     }
	ds_read_b128 v[88:91], v93
	global_load_dwordx2 v[150:151], v[50:51], off offset:-16
	global_load_dwordx2 v[152:153], v[50:51], off offset:-8
	global_load_dwordx2 v[154:155], v[50:51], off
	global_load_dwordx2 v[160:161], v[50:51], off offset:8
	v_lshl_add_u64 v[50:51], v[50:51], 0, s[2:3]
	s_waitcnt lgkmcnt(0)
	global_store_dwordx4 v[42:43], v[88:91], off offset:1280
	s_waitcnt vmcnt(16)
	v_pk_mul_f32 v[162:163], v[18:19], v[144:145] op_sel_hi:[1,0]
	v_cvt_pk_bf16_f32 v164, v162, v163
	v_pk_fma_f32 v[2:3], v[18:19], v[146:147], v[2:3] op_sel_hi:[1,0,1]
	v_lshlrev_b32_e32 v166, 16, v164
	v_and_b32_e32 v167, 0xffff0000, v164
	v_lshrrev_b32_e32 v165, 16, v164
	ds_write_b16 v92, v164 offset:9472
	ds_write_b16 v92, v165 offset:9616
	v_pk_add_f32 v[48:49], v[48:49], v[166:167]
	v_pk_mul_f32 v[168:169], v[20:21], v[144:145] op_sel_hi:[1,0]
	v_cvt_pk_bf16_f32 v134, v168, v169
	v_pk_fma_f32 v[8:9], v[20:21], v[146:147], v[8:9] op_sel_hi:[1,0,1]
	v_lshlrev_b32_e32 v58, 16, v134
	v_and_b32_e32 v59, 0xffff0000, v134
	v_lshrrev_b32_e32 v135, 16, v134
	ds_write_b16 v92, v134 offset:9760
	ds_write_b16 v92, v135 offset:9904
	v_pk_add_f32 v[40:41], v[40:41], v[58:59]
	v_pk_mul_f32 v[162:163], v[24:25], v[144:145] op_sel_hi:[1,0]
	v_cvt_pk_bf16_f32 v164, v162, v163
	v_pk_fma_f32 v[10:11], v[24:25], v[146:147], v[10:11] op_sel_hi:[1,0,1]
	v_lshlrev_b32_e32 v166, 16, v164
	v_and_b32_e32 v167, 0xffff0000, v164
	v_lshrrev_b32_e32 v165, 16, v164
	ds_write_b16 v92, v164 offset:10048
	ds_write_b16 v92, v165 offset:10192
	v_pk_add_f32 v[38:39], v[38:39], v[166:167]
	v_pk_mul_f32 v[168:169], v[28:29], v[144:145] op_sel_hi:[1,0]
	v_cvt_pk_bf16_f32 v134, v168, v169
	v_pk_fma_f32 v[12:13], v[28:29], v[146:147], v[12:13] op_sel_hi:[1,0,1]
	v_lshlrev_b32_e32 v58, 16, v134
	v_and_b32_e32 v59, 0xffff0000, v134
	v_lshrrev_b32_e32 v135, 16, v134
	ds_write_b16 v92, v134 offset:10336
	ds_write_b16 v92, v135 offset:10480
	v_pk_add_f32 v[34:35], v[34:35], v[58:59]
	s_waitcnt lgkmcnt(0)
	s_barrier
	ds_read_b128 v[184:187], v93 offset:9472
	global_load_dwordx2 v[18:19], v[50:51], off offset:-16
	global_load_dwordx2 v[20:21], v[50:51], off offset:-8
	global_load_dwordx2 v[24:25], v[50:51], off
	global_load_dwordx2 v[28:29], v[50:51], off offset:8
	v_lshl_add_u64 v[50:51], v[50:51], 0, s[2:3]
	s_waitcnt lgkmcnt(0)
	global_store_dwordx4 v[42:43], v[184:187], off offset:1408
	s_waitcnt vmcnt(16)
	v_pk_mul_f32 v[162:163], v[30:31], v[144:145] op_sel_hi:[1,0]
	v_cvt_pk_bf16_f32 v164, v162, v163
	v_pk_fma_f32 v[2:3], v[30:31], v[146:147], v[2:3] op_sel_hi:[1,0,1]
	v_lshlrev_b32_e32 v166, 16, v164
	v_and_b32_e32 v167, 0xffff0000, v164
	v_lshrrev_b32_e32 v165, 16, v164
	ds_write_b16 v92, v164
	ds_write_b16 v92, v165 offset:144
	v_pk_add_f32 v[48:49], v[48:49], v[166:167]
	v_pk_mul_f32 v[168:169], v[32:33], v[144:145] op_sel_hi:[1,0]
	v_cvt_pk_bf16_f32 v134, v168, v169
	v_pk_fma_f32 v[8:9], v[32:33], v[146:147], v[8:9] op_sel_hi:[1,0,1]
	v_lshlrev_b32_e32 v58, 16, v134
	v_and_b32_e32 v59, 0xffff0000, v134
	v_lshrrev_b32_e32 v135, 16, v134
	ds_write_b16 v92, v134 offset:288
	ds_write_b16 v92, v135 offset:432
	v_pk_add_f32 v[40:41], v[40:41], v[58:59]
	v_pk_mul_f32 v[162:163], v[36:37], v[144:145] op_sel_hi:[1,0]
	v_cvt_pk_bf16_f32 v164, v162, v163
	v_pk_fma_f32 v[10:11], v[36:37], v[146:147], v[10:11] op_sel_hi:[1,0,1]
	v_lshlrev_b32_e32 v166, 16, v164
	v_and_b32_e32 v167, 0xffff0000, v164
	v_lshrrev_b32_e32 v165, 16, v164
	ds_write_b16 v92, v164 offset:576
	ds_write_b16 v92, v165 offset:720
	v_pk_add_f32 v[38:39], v[38:39], v[166:167]
	v_pk_mul_f32 v[168:169], v[56:57], v[144:145] op_sel_hi:[1,0]
	v_cvt_pk_bf16_f32 v134, v168, v169
	v_pk_fma_f32 v[12:13], v[56:57], v[146:147], v[12:13] op_sel_hi:[1,0,1]
	v_lshlrev_b32_e32 v58, 16, v134
	v_and_b32_e32 v59, 0xffff0000, v134
	v_lshrrev_b32_e32 v135, 16, v134
	ds_write_b16 v92, v134 offset:864
	ds_write_b16 v92, v135 offset:1008
	v_pk_add_f32 v[34:35], v[34:35], v[58:59]
	s_waitcnt lgkmcnt(0)
	s_barrier
; #define LAS __attribute__((address_space(3)))
; __device__ __forceinline__ bf16_t f2bf(float f) { return (bf16_t)(cvt_pk_bf16(f, 0.f) & 0xffffu); }
; __device__ __forceinline__ float bf2f(bf16_t b) { return __uint_as_float(((unsigned)b) << 16); }
; #define LBAR() do { asm volatile("s_waitcnt lgkmcnt(0)" ::: "memory"); __builtin_amdgcn_s_barrier(); asm volatile("" ::: "memory"); } while (0)
; __device__ void conv_unit(LAS unsigned char* lds, const float* src, int ld, int sn0, int nvalid, int k0, int krows,
;                           bf16_t* dst, int dn0, int Kdst, int kd0, const float* gs, const float* bs, float* c1, float* c2) {
;     ...
;     for (int kt = 0; kt < nkt; ++kt) {
;         float w[8]; const float g = gn, b = bn;
; #pragma unroll
;         for (int j = 0; j < 8; ++j) w[j] = wn[j];
;         if (kt + 1 < nkt) { const int k = k0 + (kt + 1) * 64 + kl; gn = gs ? gs[k] : 1.f; bn = bs ? bs[k] : 0.f;
; #pragma unroll
;             for (int j = 0; j < 8; ++j) wn[j] = (ng + j < nvalid) ? src[(size_t)k * ld + sn0 + ng + j] : 0.f; }
; #pragma unroll
;         for (int j = 0; j < 8; ++j) { const bf16_t wb = f2bf(w[j] * g); a1[j] += bf2f(wb); a2[j] += b * w[j]; T[(ng + j) * 72 + kl] = wb; }
;         LBAR();
;         { const int n = tid >> 3, ks = (tid & 7) * 8; const u32x4 v = *(const LAS u32x4*)(T + n * 72 + ks);
;           *(u32x4*)(dst + (size_t)(dn0 + n) * Kdst + kd0 + kt * 64 + ks) = v; }
;         LBAR();
;     }
	ds_read_b128 v[88:91], v93
	s_waitcnt lgkmcnt(0)
	global_store_dwordx4 v[42:43], v[88:91], off offset:1536
	s_waitcnt vmcnt(12)
	v_pk_mul_f32 v[162:163], v[138:139], v[144:145] op_sel_hi:[1,0]
	v_cvt_pk_bf16_f32 v164, v162, v163
	v_pk_fma_f32 v[2:3], v[138:139], v[146:147], v[2:3] op_sel_hi:[1,0,1]
	v_lshlrev_b32_e32 v166, 16, v164
	v_and_b32_e32 v167, 0xffff0000, v164
	v_lshrrev_b32_e32 v165, 16, v164
	ds_write_b16 v92, v164 offset:9472
	ds_write_b16 v92, v165 offset:9616
	v_pk_add_f32 v[48:49], v[48:49], v[166:167]
	v_pk_mul_f32 v[168:169], v[140:141], v[144:145] op_sel_hi:[1,0]
	v_cvt_pk_bf16_f32 v134, v168, v169
	v_pk_fma_f32 v[8:9], v[140:141], v[146:147], v[8:9] op_sel_hi:[1,0,1]
	v_lshlrev_b32_e32 v58, 16, v134
	v_and_b32_e32 v59, 0xffff0000, v134
	v_lshrrev_b32_e32 v135, 16, v134
	ds_write_b16 v92, v134 offset:9760
	ds_write_b16 v92, v135 offset:9904
	v_pk_add_f32 v[40:41], v[40:41], v[58:59]
	v_pk_mul_f32 v[162:163], v[142:143], v[144:145] op_sel_hi:[1,0]
	v_cvt_pk_bf16_f32 v164, v162, v163
	v_pk_fma_f32 v[10:11], v[142:143], v[146:147], v[10:11] op_sel_hi:[1,0,1]
	v_lshlrev_b32_e32 v166, 16, v164
	v_and_b32_e32 v167, 0xffff0000, v164
	v_lshrrev_b32_e32 v165, 16, v164
	ds_write_b16 v92, v164 offset:10048
	ds_write_b16 v92, v165 offset:10192
	v_pk_add_f32 v[38:39], v[38:39], v[166:167]
	v_pk_mul_f32 v[168:169], v[148:149], v[144:145] op_sel_hi:[1,0]
	v_cvt_pk_bf16_f32 v134, v168, v169
	v_pk_fma_f32 v[12:13], v[148:149], v[146:147], v[12:13] op_sel_hi:[1,0,1]
	v_lshlrev_b32_e32 v58, 16, v134
	v_and_b32_e32 v59, 0xffff0000, v134
	v_lshrrev_b32_e32 v135, 16, v134
	ds_write_b16 v92, v134 offset:10336
	ds_write_b16 v92, v135 offset:10480
	v_pk_add_f32 v[34:35], v[34:35], v[58:59]
	s_waitcnt lgkmcnt(0)
	s_barrier
	ds_read_b128 v[184:187], v93 offset:9472
	s_waitcnt lgkmcnt(0)
	global_store_dwordx4 v[42:43], v[184:187], off offset:1664
	s_waitcnt vmcnt(8)
	v_pk_mul_f32 v[162:163], v[150:151], v[144:145] op_sel_hi:[1,0]
	v_cvt_pk_bf16_f32 v164, v162, v163
	v_pk_fma_f32 v[2:3], v[150:151], v[146:147], v[2:3] op_sel_hi:[1,0,1]
	v_lshlrev_b32_e32 v166, 16, v164
	v_and_b32_e32 v167, 0xffff0000, v164
	v_lshrrev_b32_e32 v165, 16, v164
	ds_write_b16 v92, v164
	ds_write_b16 v92, v165 offset:144
	v_pk_add_f32 v[48:49], v[48:49], v[166:167]
	v_pk_mul_f32 v[168:169], v[152:153], v[144:145] op_sel_hi:[1,0]
	v_cvt_pk_bf16_f32 v134, v168, v169
	v_pk_fma_f32 v[8:9], v[152:153], v[146:147], v[8:9] op_sel_hi:[1,0,1]
	v_lshlrev_b32_e32 v58, 16, v134
	v_and_b32_e32 v59, 0xffff0000, v134
	v_lshrrev_b32_e32 v135, 16, v134
	ds_write_b16 v92, v134 offset:288
	ds_write_b16 v92, v135 offset:432
	v_pk_add_f32 v[40:41], v[40:41], v[58:59]
	v_pk_mul_f32 v[162:163], v[154:155], v[144:145] op_sel_hi:[1,0]
	v_cvt_pk_bf16_f32 v164, v162, v163
	v_pk_fma_f32 v[10:11], v[154:155], v[146:147], v[10:11] op_sel_hi:[1,0,1]
	v_lshlrev_b32_e32 v166, 16, v164
	v_and_b32_e32 v167, 0xffff0000, v164
	v_lshrrev_b32_e32 v165, 16, v164
	ds_write_b16 v92, v164 offset:576
	ds_write_b16 v92, v165 offset:720
	v_pk_add_f32 v[38:39], v[38:39], v[166:167]
	v_pk_mul_f32 v[168:169], v[160:161], v[144:145] op_sel_hi:[1,0]
	v_cvt_pk_bf16_f32 v134, v168, v169
	v_pk_fma_f32 v[12:13], v[160:161], v[146:147], v[12:13] op_sel_hi:[1,0,1]
	v_lshlrev_b32_e32 v58, 16, v134
	v_and_b32_e32 v59, 0xffff0000, v134
	v_lshrrev_b32_e32 v135, 16, v134
	ds_write_b16 v92, v134 offset:864
	ds_write_b16 v92, v135 offset:1008
	v_pk_add_f32 v[34:35], v[34:35], v[58:59]
	s_waitcnt lgkmcnt(0)
	s_barrier
	ds_read_b128 v[88:91], v93
	s_waitcnt lgkmcnt(0)
	global_store_dwordx4 v[42:43], v[88:91], off offset:1792
	s_barrier
	v_mov_b32_e32 v54, 1.0
	v_mov_b32_e32 v16, 0
